# prompt attention: PV V-fragment reads batched with counted lgkmcnt, row max via v_max3, packed subtract before exp; all vmcnt waits as in the baseline
# baseline (speedup 1.0000x reference)
.LBB0_539:
	s_lshl_b32 s2, s21, 12
	s_add_i32 s2, s7, s2
	v_add_f32_e32 v186, v1, v186
	v_add3_u32 v1, s2, v201, v200
	v_add3_u32 v234, s2, v202, v200
	v_add3_u32 v235, s2, v203, v200
	v_add3_u32 v236, s2, v204, v200
	s_waitcnt vmcnt(0)
	ds_read_b64_tr_b16 v[130:131], v1
	ds_read_b64_tr_b16 v[132:133], v1 offset:2048
	ds_read_b64_tr_b16 v[214:215], v234
	ds_read_b64_tr_b16 v[216:217], v234 offset:2048
	ds_read_b64_tr_b16 v[218:219], v235
	ds_read_b64_tr_b16 v[220:221], v235 offset:2048
	ds_read_b64_tr_b16 v[222:223], v236
	ds_read_b64_tr_b16 v[224:225], v236 offset:2048
	s_add_i32 s19, s19, 32
	v_pk_add_f32 v[152:153], v[152:153], v[170:171]
	s_waitcnt lgkmcnt(6)
	v_mfma_f32_16x16x32_bf16 v[90:93], v[130:133], v[122:125], v[90:93]
	v_add_f32_e64 v150, v150, v186
	v_add_f32_e64 v151, v151, v187
	v_add_u32_e32 v205, 0xffffff80, v205
	s_cmp_gt_u32 s20, 16
	v_mfma_f32_16x16x32_bf16 v[46:49], v[130:133], v[126:129], v[46:49]
	v_mfma_f32_16x16x32_bf16 v[30:33], v[130:133], v[114:117], v[30:33]
	v_mfma_f32_16x16x32_bf16 v[14:17], v[130:133], v[118:121], v[14:17]
	s_waitcnt lgkmcnt(4)
	v_mfma_f32_16x16x32_bf16 v[94:97], v[214:217], v[122:125], v[94:97]
	v_mfma_f32_16x16x32_bf16 v[42:45], v[214:217], v[126:129], v[42:45]
	v_mfma_f32_16x16x32_bf16 v[26:29], v[214:217], v[114:117], v[26:29]
	v_mfma_f32_16x16x32_bf16 v[10:13], v[214:217], v[118:121], v[10:13]
	s_waitcnt lgkmcnt(2)
	v_mfma_f32_16x16x32_bf16 v[86:89], v[218:221], v[122:125], v[86:89]
	v_mfma_f32_16x16x32_bf16 v[38:41], v[218:221], v[126:129], v[38:41]
	v_mfma_f32_16x16x32_bf16 v[22:25], v[218:221], v[114:117], v[22:25]
	v_mfma_f32_16x16x32_bf16 v[6:9], v[218:221], v[118:121], v[6:9]
	s_waitcnt lgkmcnt(0)
	v_mfma_f32_16x16x32_bf16 v[82:85], v[222:225], v[122:125], v[82:85]
	v_mfma_f32_16x16x32_bf16 v[34:37], v[222:225], v[126:129], v[34:37]
	v_mfma_f32_16x16x32_bf16 v[18:21], v[222:225], v[114:117], v[18:21]
	v_mfma_f32_16x16x32_bf16 v[2:5], v[222:225], v[118:121], v[2:5]
	s_cbranch_scc1 .LBB0_541
	v_mov_b64_e32 v[116:117], v[108:109]
	v_mov_b64_e32 v[148:149], v[112:113]
	v_mov_b64_e32 v[120:121], v[100:101]
	v_mov_b64_e32 v[124:125], v[104:105]
	v_mov_b64_e32 v[114:115], v[106:107]
	v_mov_b64_e32 v[146:147], v[110:111]
	v_mov_b64_e32 v[118:119], v[98:99]
	v_mov_b64_e32 v[122:123], v[102:103]
	s_branch .LBB0_525
